# speedup vs baseline: 1.0229x; 1.0048x over previous
; __device__ __forceinline__ unsigned cvt_pk_bf16(float lo, float hi) { const f32x2 v = {lo, hi}; const bf16v2 r = __builtin_convertvector(v, bf16v2); return __builtin_bit_cast(unsigned, r); }
; __device__ __forceinline__ float bf_lo(unsigned u) { return __uint_as_float(u << 16); }
; __device__ __forceinline__ float bf_hi(unsigned u) { return __uint_as_float(u & 0xffff0000u); }
; __device__ __forceinline__ int otid() { int t = threadIdx.x; asm volatile("" : "+v"(t)); return t; }
; __device__ __forceinline__ int obid() { int b = blockIdx.x; asm volatile("" : "+s"(b)); return b; }
; __device__ void attn_combine(const bf16_t* AP, const float* LSE, bf16_t* MIX) {
;     ...
;     for (int i = obid() * 512 + otid(); i < n; i += gridDim.x * 512) {
;         const int tok = i >> 7, ch = i & 127, h = ch >> 4;
;         const float l0 = LSE[((size_t)0 * T + tok) * 8 + h], l1 = LSE[((size_t)1 * T + tok) * 8 + h], l2 = LSE[((size_t)2 * T + tok) * 8 + h];
;         const float m = fmaxf(l0, fmaxf(l1, l2)); float w0 = __expf(l0 - m), w1 = __expf(l1 - m), w2 = __expf(l2 - m); const float rs = 1.0f / (w0 + w1 + w2); w0 *= rs; w1 *= rs; w2 *= rs;
;         const u32x4 a = *(const u32x4*)(AP + ((size_t)0 * T + tok) * 1024 + ch * 8), b = *(const u32x4*)(AP + ((size_t)1 * T + tok) * 1024 + ch * 8), c = *(const u32x4*)(AP + ((size_t)2 * T + tok) * 1024 + ch * 8);
;         u32x4 w;
; #pragma unroll
;         for (int e = 0; e < 4; ++e) w[e] = cvt_pk_bf16(w0 * bf_lo(a[e]) + w1 * bf_lo(b[e]) + w2 * bf_lo(c[e]), w0 * bf_hi(a[e]) + w1 * bf_hi(b[e]) + w2 * bf_hi(c[e]));
;         *(u32x4*)(MIX + (size_t)tok * DM + ch * 8) = w;
.LBB0_297:
	v_ashrrev_i32_e32 v8, 7, v10
	v_ashrrev_i32_e32 v9, 31, v8
	v_lshlrev_b64 v[12:13], 5, v[8:9]
	s_mov_b64 s[4:5], 0x6000
	v_lshl_add_u64 v[12:13], v[2:3], 0, v[12:13]
	s_nop 0
	v_lshl_add_u64 v[16:17], v[8:9], 0, s[4:5]
	global_load_dword v0, v[12:13], off
	v_lshlrev_b64 v[12:13], 5, v[16:17]
	v_lshl_add_u64 v[12:13], v[2:3], 0, v[12:13]
	s_waitcnt vmcnt(4)
	v_lshl_add_u64 v[20:21], v[8:9], 0, s[6:7]
	global_load_dword v11, v[12:13], off
	v_lshlrev_b64 v[12:13], 5, v[20:21]
	v_lshl_add_u64 v[12:13], v[2:3], 0, v[12:13]
	global_load_dword v12, v[12:13], off
	v_lshlrev_b64 v[20:21], 11, v[20:21]
	v_lshl_add_u64 v[20:21], v[4:5], 0, v[20:21]
	global_load_dwordx4 v[20:23], v[20:21], off
	v_lshlrev_b64 v[16:17], 11, v[16:17]
	v_lshl_add_u64 v[16:17], v[4:5], 0, v[16:17]
	v_lshlrev_b64 v[34:35], 11, v[8:9]
	v_lshl_add_u64 v[34:35], v[4:5], 0, v[34:35]
	global_load_dwordx4 v[36:39], v[34:35], off
	global_load_dwordx4 v[40:43], v[16:17], off
	v_add_u32_e32 v10, s67, v10
	s_waitcnt vmcnt(3)
	v_max3_f32 v13, v0, v11, v12
	v_sub_f32_e32 v0, v0, v13
	v_mul_f32_e32 v0, 0x3fb8aa3b, v0
	v_exp_f32_e32 v25, v0
	v_sub_f32_e32 v0, v11, v13
	v_mul_f32_e32 v0, 0x3fb8aa3b, v0
	v_exp_f32_e32 v24, v0
	v_sub_f32_e32 v0, v12, v13
	v_mul_f32_e32 v0, 0x3fb8aa3b, v0
	v_exp_f32_e32 v11, v0
	v_add_f32_e32 v0, v25, v24
	s_waitcnt vmcnt(2)
	v_lshlrev_b32_e32 v32, 16, v20
	v_and_b32_e32 v33, 0xffff0000, v20
	v_add_f32_e32 v0, v11, v0
	v_div_scale_f32 v12, s[4:5], v0, v0, 1.0
	v_rcp_f32_e32 v13, v12
	v_lshlrev_b32_e32 v20, 16, v21
	v_and_b32_e32 v21, 0xffff0000, v21
	s_mov_b32 s4, 0x2fffff
	v_fma_f32 v14, -v12, v13, 1.0
	v_fmac_f32_e32 v13, v14, v13
	v_div_scale_f32 v14, vcc, 1.0, v0, 1.0
	v_mul_f32_e32 v15, v14, v13
	v_fma_f32 v18, -v12, v15, v14
	v_fmac_f32_e32 v15, v18, v13
	v_fma_f32 v12, -v12, v15, v14
	v_div_fmas_f32 v12, v12, v13, v15
	v_div_fixup_f32 v0, v12, v0, 1.0
	v_pk_mul_f32 v[24:25], v[24:25], v[0:1] op_sel_hi:[1,0]
	v_mul_f32_e32 v26, v11, v0
	v_lshlrev_b64 v[8:9], 12, v[8:9]
	v_cmp_lt_i32_e32 vcc, s4, v10
	v_lshl_add_u64 v[8:9], v[6:7], 0, v[8:9]
	s_or_b64 s[2:3], vcc, s[2:3]
	s_waitcnt vmcnt(0)
	v_lshlrev_b32_e32 v30, 16, v36
	v_and_b32_e32 v29, 0xffff0000, v36
	s_waitcnt vmcnt(0)
	v_and_b32_e32 v31, 0xffff0000, v40
	v_lshlrev_b32_e32 v28, 16, v40
	v_pk_mul_f32 v[30:31], v[24:25], v[30:31] op_sel:[1,0] op_sel_hi:[0,1]
	v_pk_fma_f32 v[28:29], v[24:25], v[28:29], v[30:31]
	v_lshlrev_b32_e32 v40, 16, v37
	v_pk_fma_f32 v[28:29], v[26:27], v[32:33], v[28:29] op_sel_hi:[0,1,1]
	v_cvt_pk_bf16_f32 v36, v28, v29
	v_lshlrev_b32_e32 v28, 16, v41
	v_and_b32_e32 v41, 0xffff0000, v41
	v_and_b32_e32 v29, 0xffff0000, v37
	v_pk_mul_f32 v[40:41], v[24:25], v[40:41] op_sel:[1,0] op_sel_hi:[0,1]
	v_pk_fma_f32 v[40:41], v[24:25], v[28:29], v[40:41]
	v_lshlrev_b32_e32 v28, 16, v22
	v_pk_fma_f32 v[40:41], v[26:27], v[20:21], v[40:41] op_sel_hi:[0,1,1]
	v_lshlrev_b32_e32 v20, 16, v38
	v_and_b32_e32 v21, 0xffff0000, v42
	v_cvt_pk_bf16_f32 v37, v40, v41
	v_lshlrev_b32_e32 v40, 16, v42
	v_and_b32_e32 v41, 0xffff0000, v38
	v_pk_mul_f32 v[20:21], v[24:25], v[20:21] op_sel:[1,0] op_sel_hi:[0,1]
	v_and_b32_e32 v29, 0xffff0000, v22
	v_pk_fma_f32 v[40:41], v[24:25], v[40:41], v[20:21]
	v_lshlrev_b32_e32 v42, 16, v39
	v_pk_fma_f32 v[40:41], v[26:27], v[28:29], v[40:41] op_sel_hi:[0,1,1]
	v_cvt_pk_bf16_f32 v38, v40, v41
	v_lshlrev_b32_e32 v40, 16, v43
	v_and_b32_e32 v43, 0xffff0000, v43
	v_and_b32_e32 v41, 0xffff0000, v39
	v_pk_mul_f32 v[42:43], v[24:25], v[42:43] op_sel:[1,0] op_sel_hi:[0,1]
	v_pk_fma_f32 v[40:41], v[24:25], v[40:41], v[42:43]
	v_lshlrev_b32_e32 v42, 16, v23
	v_and_b32_e32 v43, 0xffff0000, v23
	v_pk_fma_f32 v[40:41], v[26:27], v[42:43], v[40:41] op_sel_hi:[0,1,1]
	v_cvt_pk_bf16_f32 v39, v40, v41
	global_store_dwordx4 v[8:9], v[36:39], off
	s_andn2_b64 exec, exec, s[2:3]
	s_cbranch_execnz .LBB0_297

; __device__ __forceinline__ float bf_lo(unsigned u) { return __uint_as_float(u << 16); }
; __device__ __forceinline__ float bf_hi(unsigned u) { return __uint_as_float(u & 0xffff0000u); }
; __device__ void rope_phase(bf16_t* PROJ, const f32x2* TA, const f32x2* TR, const float* qg, const float* kg) {
;     ...
;     for (int t = gw; t < T; t += nw) {
;         int start; seq_of_token(t, start); const int pos = t - start;
;         const size_t tt = (size_t)t;
;         u32x4 va[4];
; #pragma unroll
;         for (int i = 0; i < 4; ++i) va[i] = *(const u32x4*)(PROJ + pj(tt, 512 * i + 8 * lane));
;         f32x4 ca[4];
;         { const f32x4* pa = (const f32x4*)(TA + pos * 64 + 8 * (lane & 7));
; #pragma unroll
;           for (int j = 0; j < 4; ++j) ca[j] = pa[j]; }
; #pragma unroll
;         for (int i = 0; i < 4; ++i) {
;             float x[8]; float ss = 0.f;
; #pragma unroll
;             for (int e = 0; e < 4; ++e) { x[2 * e] = bf_lo(va[i][e]); x[2 * e + 1] = bf_hi(va[i][e]); ss += x[2 * e] * x[2 * e] + x[2 * e + 1] * x[2 * e + 1]; }
;             ss += __shfl_xor(ss, 1); ss += __shfl_xor(ss, 2); ss += __shfl_xor(ss, 4); ss += __shfl_xor(ss, 8);
;             const float rstd = rsqrtf(ss * (1.0f / 128.f) + EPS);
;             float y[8];
; #pragma unroll
;             for (int e = 0; e < 8; ++e) { x[e] *= rstd * (i < 2 ? gq[e] : gk[e]); }
; #pragma unroll
;             for (int e = 0; e < 8; ++e) { const float pp = __shfl_xor(x[e], 8); const float c = ca[e >> 1][(e & 1) * 2], s = ca[e >> 1][(e & 1) * 2 + 1]; y[e] = x[e] * c + sgnA * pp * s; }
.LBB0_376:
	v_and_b32_e32 v0, 0x3fff000, v74
	v_cmp_lt_i32_e32 vcc, s15, v74
	v_add_u32_e32 v74, s90, v74
	s_nop 0
	v_cndmask_b32_e32 v0, 0, v0, vcc
	v_add_co_u32_e32 v56, vcc, 0xfb800000, v48
	v_lshlrev_b32_e32 v0, 6, v0
	s_nop 0
	v_addc_co_u32_e32 v57, vcc, -1, v49, vcc
	global_load_dwordx4 v[58:61], v[56:57], off
	v_add_co_u32_e32 v54, vcc, 0xfd000000, v48
	v_sub_u32_e32 v18, v79, v0
	s_waitcnt lgkmcnt(0)
	v_addc_co_u32_e32 v55, vcc, -1, v49, vcc
	v_add_co_u32_e32 v50, vcc, 0xfe800000, v48
	v_ashrrev_i32_e32 v19, 31, v18
	global_load_dwordx4 v[42:45], v[54:55], off
	v_addc_co_u32_e32 v51, vcc, -1, v49, vcc
	v_lshl_add_u64 v[30:31], v[18:19], 3, v[46:47]
	global_load_dwordx4 v[38:41], v[50:51], off
	global_load_dwordx4 v[34:37], v[48:49], off
	global_load_dwordx4 v[18:21], v[30:31], off offset:48
	global_load_dwordx4 v[22:25], v[30:31], off offset:32
	global_load_dwordx4 v[26:29], v[30:31], off offset:16
	s_nop 0
	global_load_dwordx4 v[30:33], v[30:31], off
	v_add_u32_e32 v79, s67, v79
	s_waitcnt vmcnt(7)
	v_lshlrev_b32_e32 v62, 16, v61
	v_lshlrev_b32_e32 v64, 16, v60
	v_and_b32_e32 v63, 0xffff0000, v61
	v_and_b32_e32 v65, 0xffff0000, v60
	v_mov_b32_e32 v52, v62
	v_mov_b32_e32 v53, v64
	v_pk_mul_f32 v[52:53], v[52:53], v[52:53]
	v_mov_b32_e32 v60, v63
	v_mov_b32_e32 v61, v65
	v_lshlrev_b32_e32 v68, 16, v59
	v_lshlrev_b32_e32 v70, 16, v58
	v_pk_fma_f32 v[72:73], v[60:61], v[60:61], v[52:53]
	v_and_b32_e32 v69, 0xffff0000, v59
	v_and_b32_e32 v71, 0xffff0000, v58
	v_mov_b32_e32 v52, v70
	v_mov_b32_e32 v53, v68
	v_pk_mul_f32 v[52:53], v[52:53], v[52:53]
	v_mov_b32_e32 v58, v71
	v_mov_b32_e32 v59, v69
	v_pk_fma_f32 v[80:81], v[58:59], v[58:59], v[52:53]
	s_waitcnt vmcnt(6)
	v_lshlrev_b32_e32 v58, 16, v45
	v_lshlrev_b32_e32 v60, 16, v44
	s_waitcnt vmcnt(0)
	v_mov_b32_e32 v52, v30
	v_mov_b32_e32 v53, v32
	v_mov_b32_e32 v32, v31
	v_mov_b32_e32 v30, v26
	v_mov_b32_e32 v31, v28
	v_mov_b32_e32 v28, v27
	v_mov_b32_e32 v26, v22
	v_mov_b32_e32 v27, v24
	v_mov_b32_e32 v24, v23
	v_mov_b32_e32 v22, v18
	v_mov_b32_e32 v23, v20
	v_mov_b32_e32 v20, v19
	v_and_b32_e32 v59, 0xffff0000, v45
	v_and_b32_e32 v61, 0xffff0000, v44
	v_mov_b32_e32 v18, v58
	v_mov_b32_e32 v19, v60
	v_pk_mul_f32 v[18:19], v[18:19], v[18:19]
	v_mov_b32_e32 v44, v59
	v_mov_b32_e32 v45, v61
	v_pk_fma_f32 v[18:19], v[44:45], v[44:45], v[18:19]
	v_lshlrev_b32_e32 v44, 16, v43
	v_lshlrev_b32_e32 v66, 16, v42
	v_and_b32_e32 v45, 0xffff0000, v43
	v_and_b32_e32 v67, 0xffff0000, v42
	v_mov_b32_e32 v42, v66
	v_mov_b32_e32 v43, v44
	v_pk_mul_f32 v[42:43], v[42:43], v[42:43]
	v_mov_b32_e32 v82, v67
	v_mov_b32_e32 v83, v45
	v_pk_fma_f32 v[42:43], v[82:83], v[82:83], v[42:43]
	v_mov_b32_e32 v83, v80
	v_mov_b32_e32 v82, v42
	v_mov_b32_e32 v80, v43
	v_pk_add_f32 v[42:43], v[82:83], v[80:81]
	v_mov_b32_e32 v80, v19
	v_mov_b32_e32 v81, v73
	v_pk_add_f32 v[42:43], v[80:81], v[42:43]
	v_mov_b32_e32 v19, v72
	v_pk_add_f32 v[18:19], v[18:19], v[42:43]
	s_nop 1
	v_mov_b32_dpp v43, v19 quad_perm:[1,0,3,2] row_mask:0xf bank_mask:0xf
	s_nop 1
	v_mov_b32_dpp v42, v18 quad_perm:[1,0,3,2] row_mask:0xf bank_mask:0xf
	s_waitcnt lgkmcnt(0)
	v_pk_add_f32 v[18:19], v[18:19], v[42:43]
	s_nop 1
	v_mov_b32_dpp v43, v19 quad_perm:[2,3,0,1] row_mask:0xf bank_mask:0xf
	s_nop 1
	v_mov_b32_dpp v42, v18 quad_perm:[2,3,0,1] row_mask:0xf bank_mask:0xf
	s_waitcnt lgkmcnt(0)
	v_pk_add_f32 v[18:19], v[18:19], v[42:43]
	s_nop 1
	v_mov_b32_dpp v100, v19 quad_perm:[3,2,1,0] row_mask:0xf bank_mask:0xf
	s_nop 1
	v_mov_b32_dpp v43, v100 row_half_mirror row_mask:0xf bank_mask:0xf
	s_nop 1
	v_mov_b32_dpp v100, v18 quad_perm:[3,2,1,0] row_mask:0xf bank_mask:0xf
	s_nop 1
	v_mov_b32_dpp v42, v100 row_half_mirror row_mask:0xf bank_mask:0xf
	s_waitcnt lgkmcnt(0)
	v_pk_add_f32 v[18:19], v[18:19], v[42:43]
	s_nop 1
	v_mov_b32_dpp v43, v19 row_ror:8 row_mask:0xf bank_mask:0xf
	s_nop 1
	v_mov_b32_dpp v42, v18 row_ror:8 row_mask:0xf bank_mask:0xf
	s_waitcnt lgkmcnt(0)
	v_pk_add_f32 v[42:43], v[18:19], v[42:43]
	v_mov_b64_e32 v[18:19], s[18:19]
	v_pk_fma_f32 v[42:43], v[42:43], s[20:21], v[18:19] op_sel_hi:[1,0,0]
	s_nop 0
	v_mul_f32_e32 v0, 0x4b800000, v43
	v_cmp_gt_f32_e64 s[0:1], s14, v43
	v_cmp_gt_f32_e32 vcc, s14, v42
	s_nop 0
	v_cndmask_b32_e64 v0, v43, v0, s[0:1]
	v_rsq_f32_e32 v0, v0
	s_nop 0
	v_mul_f32_e32 v43, 0x45800000, v0
	v_cndmask_b32_e64 v0, v0, v43, s[0:1]
	v_pk_mul_f32 v[72:73], v[6:7], v[0:1] op_sel_hi:[1,0]
	s_nop 0
	v_pk_mul_f32 v[70:71], v[72:73], v[70:71]
	v_pk_mul_f32 v[72:73], v[8:9], v[0:1] op_sel_hi:[1,0]
	s_nop 1
	v_mov_b32_dpp v43, v71 row_ror:8 row_mask:0xf bank_mask:0xf
	v_pk_mul_f32 v[68:69], v[72:73], v[68:69]
	v_pk_mul_f32 v[72:73], v[2:3], v[0:1] op_sel_hi:[1,0]
	s_nop 0
	v_pk_mul_f32 v[64:65], v[72:73], v[64:65]
	v_pk_mul_f32 v[72:73], v[4:5], v[0:1] op_sel_hi:[1,0]
	s_nop 1
	v_mov_b32_dpp v0, v70 row_ror:8 row_mask:0xf bank_mask:0xf
	v_pk_mul_f32 v[62:63], v[72:73], v[62:63]
	v_pk_mul_f32 v[70:71], v[52:53], v[70:71]
	s_waitcnt lgkmcnt(1)
	v_cndmask_b32_e64 v73, v43, -v43, s[38:39]
	s_nop 1
	v_mov_b32_dpp v43, v69 row_ror:8 row_mask:0xf bank_mask:0xf
	s_waitcnt lgkmcnt(1)
	v_cndmask_b32_e64 v72, v0, -v0, s[38:39]
	s_nop 1
	v_mov_b32_dpp v0, v68 row_ror:8 row_mask:0xf bank_mask:0xf
	v_pk_fma_f32 v[70:71], v[32:33], v[72:73], v[70:71]
	v_pk_mul_f32 v[68:69], v[30:31], v[68:69]
	s_waitcnt lgkmcnt(1)
	v_cndmask_b32_e64 v73, v43, -v43, s[38:39]
	s_nop 1
	v_mov_b32_dpp v43, v65 row_ror:8 row_mask:0xf bank_mask:0xf
	s_waitcnt lgkmcnt(1)
	v_cndmask_b32_e64 v72, v0, -v0, s[38:39]
	s_nop 1
	v_mov_b32_dpp v0, v64 row_ror:8 row_mask:0xf bank_mask:0xf
	v_pk_fma_f32 v[68:69], v[28:29], v[72:73], v[68:69]
	v_pk_mul_f32 v[64:65], v[26:27], v[64:65]
	s_waitcnt lgkmcnt(1)
; __device__ __forceinline__ unsigned cvt_pk_bf16(float lo, float hi) { const f32x2 v = {lo, hi}; const bf16v2 r = __builtin_convertvector(v, bf16v2); return __builtin_bit_cast(unsigned, r); }
; __device__ __forceinline__ float bf_lo(unsigned u) { return __uint_as_float(u << 16); }
; __device__ __forceinline__ float bf_hi(unsigned u) { return __uint_as_float(u & 0xffff0000u); }
; __device__ void rope_phase(bf16_t* PROJ, const f32x2* TA, const f32x2* TR, const float* qg, const float* kg) {
;     ...
;         for (int i = 0; i < 4; ++i) {
;             float x[8]; float ss = 0.f;
; #pragma unroll
;             for (int e = 0; e < 4; ++e) { x[2 * e] = bf_lo(va[i][e]); x[2 * e + 1] = bf_hi(va[i][e]); ss += x[2 * e] * x[2 * e] + x[2 * e + 1] * x[2 * e + 1]; }
;             ss += __shfl_xor(ss, 1); ss += __shfl_xor(ss, 2); ss += __shfl_xor(ss, 4); ss += __shfl_xor(ss, 8);
;             const float rstd = rsqrtf(ss * (1.0f / 128.f) + EPS);
;             float y[8];
; #pragma unroll
;             for (int e = 0; e < 8; ++e) { x[e] *= rstd * (i < 2 ? gq[e] : gk[e]); }
; #pragma unroll
;             for (int e = 0; e < 8; ++e) { const float pp = __shfl_xor(x[e], 8); const float c = ca[e >> 1][(e & 1) * 2], s = ca[e >> 1][(e & 1) * 2 + 1]; y[e] = x[e] * c + sgnA * pp * s; }
;             u32x4 w;
; #pragma unroll
;             for (int e = 0; e < 4; ++e) w[e] = cvt_pk_bf16(y[2 * e], y[2 * e + 1]);
;             *(u32x4*)(PROJ + pj(tt, 512 * i + 8 * lane)) = w;
	v_cndmask_b32_e64 v73, v43, -v43, s[38:39]
	s_nop 1
	v_mov_b32_dpp v43, v63 row_ror:8 row_mask:0xf bank_mask:0xf
	s_waitcnt lgkmcnt(1)
	v_cndmask_b32_e64 v72, v0, -v0, s[38:39]
	s_nop 1
	v_mov_b32_dpp v0, v62 row_ror:8 row_mask:0xf bank_mask:0xf
	v_pk_fma_f32 v[64:65], v[24:25], v[72:73], v[64:65]
	v_pk_mul_f32 v[62:63], v[22:23], v[62:63]
	s_waitcnt lgkmcnt(1)
	v_cndmask_b32_e64 v73, v43, -v43, s[38:39]
	v_cvt_pk_bf16_f32 v64, v64, v65
	s_waitcnt lgkmcnt(0)
	v_cndmask_b32_e64 v72, v0, -v0, s[38:39]
	v_mul_f32_e32 v0, 0x4b800000, v42
	v_cndmask_b32_e32 v0, v42, v0, vcc
	v_rsq_f32_e32 v0, v0
	v_pk_fma_f32 v[72:73], v[20:21], v[72:73], v[62:63]
	v_cvt_pk_bf16_f32 v62, v70, v71
	v_cvt_pk_bf16_f32 v63, v68, v69
	v_mul_f32_e32 v42, 0x45800000, v0
	v_cvt_pk_bf16_f32 v65, v72, v73
	v_cndmask_b32_e32 v0, v0, v42, vcc
	global_store_dwordx4 v[56:57], v[62:65], off
	v_pk_mul_f32 v[56:57], v[8:9], v[0:1] op_sel_hi:[1,0]
	v_pk_mul_f32 v[42:43], v[6:7], v[0:1] op_sel_hi:[1,0]
	v_pk_mul_f32 v[44:45], v[56:57], v[44:45]
	v_pk_mul_f32 v[56:57], v[2:3], v[0:1] op_sel_hi:[1,0]
	v_pk_mul_f32 v[42:43], v[42:43], v[66:67]
	v_pk_mul_f32 v[56:57], v[56:57], v[60:61]
	v_pk_mul_f32 v[60:61], v[4:5], v[0:1] op_sel_hi:[1,0]
	s_nop 1
	v_mov_b32_dpp v0, v42 row_ror:8 row_mask:0xf bank_mask:0xf
	v_pk_mul_f32 v[58:59], v[60:61], v[58:59]
	s_nop 1
	v_mov_b32_dpp v60, v43 row_ror:8 row_mask:0xf bank_mask:0xf
	v_pk_mul_f32 v[42:43], v[52:53], v[42:43]
	s_waitcnt lgkmcnt(0)
	v_cndmask_b32_e64 v61, v60, -v60, s[38:39]
	v_cndmask_b32_e64 v60, v0, -v0, s[38:39]
	v_pk_fma_f32 v[42:43], v[32:33], v[60:61], v[42:43]
	s_nop 1
	v_mov_b32_dpp v0, v44 row_ror:8 row_mask:0xf bank_mask:0xf
	s_nop 1
	v_mov_b32_dpp v60, v45 row_ror:8 row_mask:0xf bank_mask:0xf
	v_pk_mul_f32 v[44:45], v[30:31], v[44:45]
	v_cvt_pk_bf16_f32 v42, v42, v43
	s_waitcnt lgkmcnt(0)
	v_cndmask_b32_e64 v61, v60, -v60, s[38:39]
	v_cndmask_b32_e64 v60, v0, -v0, s[38:39]
	v_pk_fma_f32 v[44:45], v[28:29], v[60:61], v[44:45]
	s_nop 1
	v_mov_b32_dpp v0, v56 row_ror:8 row_mask:0xf bank_mask:0xf
	s_nop 1
	v_mov_b32_dpp v60, v57 row_ror:8 row_mask:0xf bank_mask:0xf
	v_pk_mul_f32 v[56:57], v[26:27], v[56:57]
	v_cvt_pk_bf16_f32 v43, v44, v45
	s_waitcnt lgkmcnt(0)
	v_cndmask_b32_e64 v61, v60, -v60, s[38:39]
	v_cndmask_b32_e64 v60, v0, -v0, s[38:39]
	v_pk_fma_f32 v[56:57], v[24:25], v[60:61], v[56:57]
	s_nop 1
	v_mov_b32_dpp v0, v58 row_ror:8 row_mask:0xf bank_mask:0xf
	s_nop 1
	v_mov_b32_dpp v60, v59 row_ror:8 row_mask:0xf bank_mask:0xf
	v_pk_mul_f32 v[58:59], v[22:23], v[58:59]
	v_cvt_pk_bf16_f32 v44, v56, v57
	s_waitcnt lgkmcnt(0)
	v_cndmask_b32_e64 v61, v60, -v60, s[38:39]
	v_cndmask_b32_e64 v60, v0, -v0, s[38:39]
	v_pk_fma_f32 v[58:59], v[20:21], v[60:61], v[58:59]
	v_lshlrev_b32_e32 v60, 16, v38
	v_cvt_pk_bf16_f32 v45, v58, v59
	global_store_dwordx4 v[54:55], v[42:45], off
	v_lshlrev_b32_e32 v54, 16, v40
	v_and_b32_e32 v55, 0xffff0000, v40
	v_lshlrev_b32_e32 v44, 16, v41
	v_and_b32_e32 v45, 0xffff0000, v41
	v_mov_b32_e32 v40, v44
	v_mov_b32_e32 v41, v54
	v_lshlrev_b32_e32 v58, 16, v39
	v_pk_mul_f32 v[40:41], v[40:41], v[40:41]
	v_mov_b32_e32 v42, v45
	v_mov_b32_e32 v43, v55
	v_and_b32_e32 v59, 0xffff0000, v39
	v_and_b32_e32 v61, 0xffff0000, v38
	v_mov_b32_e32 v38, v60
	v_mov_b32_e32 v39, v58
	v_pk_fma_f32 v[56:57], v[42:43], v[42:43], v[40:41]
	v_pk_mul_f32 v[38:39], v[38:39], v[38:39]
	v_mov_b32_e32 v40, v61
	v_mov_b32_e32 v41, v59
	v_pk_fma_f32 v[62:63], v[40:41], v[40:41], v[38:39]
	v_lshlrev_b32_e32 v38, 16, v37
	v_lshlrev_b32_e32 v40, 16, v36
	v_and_b32_e32 v39, 0xffff0000, v37
	v_and_b32_e32 v41, 0xffff0000, v36
	v_mov_b32_e32 v36, v38
	v_mov_b32_e32 v37, v40
	v_pk_mul_f32 v[36:37], v[36:37], v[36:37]
	v_mov_b32_e32 v42, v39
	v_mov_b32_e32 v43, v41
	v_pk_fma_f32 v[64:65], v[42:43], v[42:43], v[36:37]
	v_lshlrev_b32_e32 v36, 16, v35
	v_lshlrev_b32_e32 v42, 16, v34
	v_and_b32_e32 v37, 0xffff0000, v35
	v_and_b32_e32 v43, 0xffff0000, v34
	v_mov_b32_e32 v34, v42
	v_mov_b32_e32 v35, v36
	v_pk_mul_f32 v[34:35], v[34:35], v[34:35]
	v_mov_b32_e32 v66, v43
	v_mov_b32_e32 v67, v37
	v_pk_fma_f32 v[34:35], v[66:67], v[66:67], v[34:35]
	v_mov_b32_e32 v67, v62
	v_mov_b32_e32 v66, v34
	v_mov_b32_e32 v62, v35
	v_pk_add_f32 v[34:35], v[66:67], v[62:63]
	v_mov_b32_e32 v62, v65
	v_mov_b32_e32 v63, v57
	v_pk_add_f32 v[34:35], v[62:63], v[34:35]
	v_mov_b32_e32 v65, v56
	v_pk_add_f32 v[34:35], v[64:65], v[34:35]
	s_nop 1
	v_mov_b32_dpp v57, v35 quad_perm:[1,0,3,2] row_mask:0xf bank_mask:0xf
	s_nop 1
	v_mov_b32_dpp v56, v34 quad_perm:[1,0,3,2] row_mask:0xf bank_mask:0xf
	s_waitcnt lgkmcnt(0)
	v_pk_add_f32 v[34:35], v[34:35], v[56:57]
	s_nop 1
	v_mov_b32_dpp v57, v35 quad_perm:[2,3,0,1] row_mask:0xf bank_mask:0xf
	s_nop 1
	v_mov_b32_dpp v56, v34 quad_perm:[2,3,0,1] row_mask:0xf bank_mask:0xf
	s_waitcnt lgkmcnt(0)
	v_pk_add_f32 v[34:35], v[34:35], v[56:57]
	s_nop 1
	v_mov_b32_dpp v100, v35 quad_perm:[3,2,1,0] row_mask:0xf bank_mask:0xf
	s_nop 1
	v_mov_b32_dpp v57, v100 row_half_mirror row_mask:0xf bank_mask:0xf
	s_nop 1
	v_mov_b32_dpp v100, v34 quad_perm:[3,2,1,0] row_mask:0xf bank_mask:0xf
	s_nop 1
	v_mov_b32_dpp v56, v100 row_half_mirror row_mask:0xf bank_mask:0xf
	s_waitcnt lgkmcnt(0)
; __device__ __forceinline__ unsigned cvt_pk_bf16(float lo, float hi) { const f32x2 v = {lo, hi}; const bf16v2 r = __builtin_convertvector(v, bf16v2); return __builtin_bit_cast(unsigned, r); }
; __device__ __forceinline__ float bf_lo(unsigned u) { return __uint_as_float(u << 16); }
; __device__ __forceinline__ float bf_hi(unsigned u) { return __uint_as_float(u & 0xffff0000u); }
; __device__ void rope_phase(bf16_t* PROJ, const f32x2* TA, const f32x2* TR, const float* qg, const float* kg) {
;     ...
;         for (int i = 0; i < 4; ++i) {
;             float x[8]; float ss = 0.f;
; #pragma unroll
;             for (int e = 0; e < 4; ++e) { x[2 * e] = bf_lo(va[i][e]); x[2 * e + 1] = bf_hi(va[i][e]); ss += x[2 * e] * x[2 * e] + x[2 * e + 1] * x[2 * e + 1]; }
;             ss += __shfl_xor(ss, 1); ss += __shfl_xor(ss, 2); ss += __shfl_xor(ss, 4); ss += __shfl_xor(ss, 8);
;             const float rstd = rsqrtf(ss * (1.0f / 128.f) + EPS);
;             float y[8];
; #pragma unroll
;             for (int e = 0; e < 8; ++e) { x[e] *= rstd * (i < 2 ? gq[e] : gk[e]); }
; #pragma unroll
;             for (int e = 0; e < 8; ++e) { const float pp = __shfl_xor(x[e], 8); const float c = ca[e >> 1][(e & 1) * 2], s = ca[e >> 1][(e & 1) * 2 + 1]; y[e] = x[e] * c + sgnA * pp * s; }
;             u32x4 w;
; #pragma unroll
;             for (int e = 0; e < 4; ++e) w[e] = cvt_pk_bf16(y[2 * e], y[2 * e + 1]);
;             *(u32x4*)(PROJ + pj(tt, 512 * i + 8 * lane)) = w;
	v_pk_add_f32 v[34:35], v[34:35], v[56:57]
	s_nop 1
	v_mov_b32_dpp v57, v35 row_ror:8 row_mask:0xf bank_mask:0xf
	s_nop 1
	v_mov_b32_dpp v56, v34 row_ror:8 row_mask:0xf bank_mask:0xf
	s_waitcnt lgkmcnt(0)
	v_pk_add_f32 v[34:35], v[34:35], v[56:57]
	s_nop 0
	v_pk_fma_f32 v[18:19], v[34:35], s[20:21], v[18:19] op_sel_hi:[1,0,0]
	s_nop 0
	v_mul_f32_e32 v0, 0x4b800000, v19
	v_cmp_gt_f32_e64 s[0:1], s14, v19
	v_cmp_gt_f32_e32 vcc, s14, v18
	s_nop 0
	v_cndmask_b32_e64 v0, v19, v0, s[0:1]
	v_rsq_f32_e32 v0, v0
	s_nop 0
	v_mul_f32_e32 v19, 0x45800000, v0
	v_cndmask_b32_e64 v0, v0, v19, s[0:1]
	v_pk_mul_f32 v[34:35], v[14:15], v[0:1] op_sel_hi:[1,0]
	v_pk_mul_f32 v[56:57], v[16:17], v[0:1] op_sel_hi:[1,0]
	v_pk_mul_f32 v[34:35], v[34:35], v[60:61]
	v_pk_mul_f32 v[56:57], v[56:57], v[58:59]
	v_pk_mul_f32 v[58:59], v[10:11], v[0:1] op_sel_hi:[1,0]
	s_nop 1
	v_mov_b32_dpp v19, v35 row_ror:8 row_mask:0xf bank_mask:0xf
	v_pk_mul_f32 v[54:55], v[58:59], v[54:55]
	v_pk_mul_f32 v[58:59], v[12:13], v[0:1] op_sel_hi:[1,0]
	s_nop 1
	v_mov_b32_dpp v0, v34 row_ror:8 row_mask:0xf bank_mask:0xf
	v_pk_mul_f32 v[44:45], v[58:59], v[44:45]
	v_pk_mul_f32 v[34:35], v[52:53], v[34:35]
	s_waitcnt lgkmcnt(1)
	v_cndmask_b32_e64 v59, v19, -v19, s[38:39]
	s_nop 1
	v_mov_b32_dpp v19, v57 row_ror:8 row_mask:0xf bank_mask:0xf
	s_waitcnt lgkmcnt(1)
	v_cndmask_b32_e64 v58, v0, -v0, s[38:39]
	s_nop 1
	v_mov_b32_dpp v0, v56 row_ror:8 row_mask:0xf bank_mask:0xf
	v_pk_fma_f32 v[34:35], v[32:33], v[58:59], v[34:35]
	v_pk_mul_f32 v[56:57], v[30:31], v[56:57]
	s_waitcnt lgkmcnt(1)
	v_cndmask_b32_e64 v59, v19, -v19, s[38:39]
	s_nop 1
	v_mov_b32_dpp v19, v55 row_ror:8 row_mask:0xf bank_mask:0xf
	s_waitcnt lgkmcnt(1)
	v_cndmask_b32_e64 v58, v0, -v0, s[38:39]
	s_nop 1
	v_mov_b32_dpp v0, v54 row_ror:8 row_mask:0xf bank_mask:0xf
	v_pk_fma_f32 v[56:57], v[28:29], v[58:59], v[56:57]
	v_pk_mul_f32 v[54:55], v[26:27], v[54:55]
	s_waitcnt lgkmcnt(1)
	v_cndmask_b32_e64 v59, v19, -v19, s[38:39]
	s_nop 1
	v_mov_b32_dpp v19, v45 row_ror:8 row_mask:0xf bank_mask:0xf
	s_waitcnt lgkmcnt(1)
	v_cndmask_b32_e64 v58, v0, -v0, s[38:39]
	s_nop 1
	v_mov_b32_dpp v0, v44 row_ror:8 row_mask:0xf bank_mask:0xf
	v_pk_fma_f32 v[58:59], v[24:25], v[58:59], v[54:55]
	v_pk_mul_f32 v[44:45], v[22:23], v[44:45]
	s_waitcnt lgkmcnt(1)
	v_cndmask_b32_e64 v55, v19, -v19, s[38:39]
	s_waitcnt lgkmcnt(0)
	v_cndmask_b32_e64 v54, v0, -v0, s[38:39]
	v_mul_f32_e32 v0, 0x4b800000, v18
	v_cndmask_b32_e32 v0, v18, v0, vcc
	v_rsq_f32_e32 v0, v0
	v_pk_fma_f32 v[44:45], v[20:21], v[54:55], v[44:45]
	v_cvt_pk_bf16_f32 v54, v34, v35
	v_cvt_pk_bf16_f32 v55, v56, v57
	v_mul_f32_e32 v18, 0x45800000, v0
	v_cndmask_b32_e32 v0, v0, v18, vcc
	v_pk_mul_f32 v[34:35], v[16:17], v[0:1] op_sel_hi:[1,0]
	v_pk_mul_f32 v[18:19], v[14:15], v[0:1] op_sel_hi:[1,0]
	v_pk_mul_f32 v[34:35], v[34:35], v[36:37]
	v_pk_mul_f32 v[36:37], v[10:11], v[0:1] op_sel_hi:[1,0]
	v_pk_mul_f32 v[18:19], v[18:19], v[42:43]
	v_pk_mul_f32 v[36:37], v[36:37], v[40:41]
	v_pk_mul_f32 v[40:41], v[12:13], v[0:1] op_sel_hi:[1,0]
	s_nop 1
	v_mov_b32_dpp v0, v18 row_ror:8 row_mask:0xf bank_mask:0xf
	v_pk_mul_f32 v[38:39], v[40:41], v[38:39]
	s_nop 1
	v_mov_b32_dpp v40, v19 row_ror:8 row_mask:0xf bank_mask:0xf
	v_pk_mul_f32 v[18:19], v[52:53], v[18:19]
	v_pk_mul_f32 v[30:31], v[30:31], v[34:35]
	v_pk_mul_f32 v[26:27], v[26:27], v[36:37]
	v_pk_mul_f32 v[22:23], v[22:23], v[38:39]
	s_waitcnt lgkmcnt(0)
	v_cndmask_b32_e64 v41, v40, -v40, s[38:39]
	v_cndmask_b32_e64 v40, v0, -v0, s[38:39]
	v_pk_fma_f32 v[18:19], v[32:33], v[40:41], v[18:19]
	s_nop 1
	v_mov_b32_dpp v0, v34 row_ror:8 row_mask:0xf bank_mask:0xf
	s_nop 1
	v_mov_b32_dpp v32, v35 row_ror:8 row_mask:0xf bank_mask:0xf
	v_cvt_pk_bf16_f32 v18, v18, v19
	v_cmp_lt_i32_e32 vcc, s16, v74
	v_cvt_pk_bf16_f32 v56, v58, v59
	v_cvt_pk_bf16_f32 v57, v44, v45
	s_waitcnt lgkmcnt(0)
	v_cndmask_b32_e64 v33, v32, -v32, s[38:39]
	v_cndmask_b32_e64 v32, v0, -v0, s[38:39]
	v_pk_fma_f32 v[28:29], v[28:29], v[32:33], v[30:31]
	s_nop 1
	v_mov_b32_dpp v0, v36 row_ror:8 row_mask:0xf bank_mask:0xf
	s_nop 1
	v_mov_b32_dpp v30, v37 row_ror:8 row_mask:0xf bank_mask:0xf
	v_cvt_pk_bf16_f32 v19, v28, v29
	s_or_b64 s[4:5], vcc, s[4:5]
	global_store_dwordx4 v[50:51], v[54:57], off
	s_waitcnt lgkmcnt(0)
	v_cndmask_b32_e64 v31, v30, -v30, s[38:39]
	v_cndmask_b32_e64 v30, v0, -v0, s[38:39]
	v_pk_fma_f32 v[24:25], v[24:25], v[30:31], v[26:27]
	s_nop 1
	v_mov_b32_dpp v0, v38 row_ror:8 row_mask:0xf bank_mask:0xf
	s_nop 1
	v_mov_b32_dpp v26, v39 row_ror:8 row_mask:0xf bank_mask:0xf
	s_waitcnt lgkmcnt(0)
	v_cndmask_b32_e64 v27, v26, -v26, s[38:39]
	v_cndmask_b32_e64 v26, v0, -v0, s[38:39]
	v_pk_fma_f32 v[22:23], v[20:21], v[26:27], v[22:23]
	v_cvt_pk_bf16_f32 v20, v24, v25
	v_cvt_pk_bf16_f32 v21, v22, v23
	global_store_dwordx4 v[48:49], v[18:21], off
	v_lshl_add_u64 v[48:49], v[48:49], 0, s[12:13]
	s_andn2_b64 exec, exec, s[4:5]
	s_cbranch_execnz .LBB0_376
